# in-proj K-loop: first iteration peeled with srcC=0 (no accumulator zeroing movs); chain waits relaxed
# speedup vs baseline: 1.0041x; 1.0041x over previous
; #define GAS __attribute__((address_space(1)))
; #define PG8_STAGE(bufoff, gbase, voff) do { _Pragma("unroll") for (int _i = 0; _i < 2; ++_i) \
;         __builtin_amdgcn_global_load_lds((const GAS unsigned*)((const GAS char*)(gbase) + (voff)[_i]), (LAS unsigned*)(lds + (bufoff) + ldsw + _i * 8192), 16, 0, 0); } while (0)
; #define PG8_LDA(dst, b, h) do { _Pragma("unroll") for (int m = 0; m < 4; ++m) _Pragma("unroll") for (int k = 0; k < 2; ++k) dst[m][k] = *(const LAS bf16x8*)(lds + PG8_SA(b, h) + aoff + m * 2048 + k * 1024); } while (0)
; #define PG8_LDB(dst, b, h) do { _Pragma("unroll") for (int n = 0; n < 2; ++n) _Pragma("unroll") for (int k = 0; k < 2; ++k) dst[n][k] = *(const LAS bf16x8*)(lds + PG8_SB(b, h) + boff + n * 2048 + k * 1024); } while (0)
;     ...
;     for (;;) {
;         const bool has_next = S.template next<MODE>(ui + 1, nxt);
;         const GAS char* nA = has_next ? (const GAS char*)(g.A + (size_t)nxt.seg * g.a_seg) + (size_t)nxt.pm * tstep + (MODE ? (size_t)nxt.k0 * kstep : 0) : cA; const GAS char* nB = has_next ? (const GAS char*)(g.Bt + (size_t)nxt.seg * g.b_seg) + (size_t)nxt.pn * tstep + (MODE ? (size_t)nxt.k0 * kstep : 0) : cB;
;         const int nt = MODE == 0 ? K / BK : cur.nk;
;         for (int t = 0; t < nt; t += 2) {
;             const bool last = (t == nt - 2);
;             const GAS char* a1 = cA + (size_t)(t + 1) * kstep;
;             const GAS char* a2 = last ? nA : cA + (size_t)(t + 2) * kstep; const GAS char* b2 = last ? nB : cB + (size_t)(t + 2) * kstep;
;             const GAS char* a3 = a2 + kstep; const GAS char* b3 = b2 + kstep;
;             PG8_LDB(B0, 0, 0); PG8_LDB(B1, 0, 1); PG8_SCHED; PG8_LDA(At, 0, 0); PG8_STAGE(PG8_SA(1, 1), a1 + hstep, voffA);
;             PG8_WAIT_V(8); PG8_WAIT_L(0); PG8_BAR; PG8_MMA(0, 0, At, B0); PG8_MMA(0, 1, At, B1); PG8_BAR; PG8_SCHED;
;             PG8_LDA(At, 0, 1); PG8_STAGE(PG8_SB(0, 0), b2, voffB); PG8_STAGE(PG8_SB(0, 1), b2 + hstep, voffB); PG8_STAGE(PG8_SA(0, 0), a2, voffA);
;             PG8_WAIT_V(8); PG8_WAIT_L(0); PG8_BAR; PG8_MMA(1, 0, At, B0); PG8_MMA(1, 1, At, B1); PG8_BAR; PG8_SCHED;
;             PG8_LDB(B0, 1, 0); PG8_LDB(B1, 1, 1); PG8_SCHED; PG8_LDA(At, 1, 0); PG8_STAGE(PG8_SA(0, 1), a2 + hstep, voffA);
;             PG8_WAIT_V(8); PG8_WAIT_L(0); PG8_BAR; PG8_MMA(0, 0, At, B0); PG8_MMA(0, 1, At, B1); PG8_BAR; PG8_SCHED;
.LBB0_189:
	s_ashr_i32 s89, s88, 31
	s_lshl_b64 s[8:9], s[88:89], 19
	s_add_u32 s8, s13, s8
	s_addc_u32 s9, s14, s9
	s_and_b64 s[26:27], s[60:61], exec
	s_cselect_b32 s17, s9, s37
	s_cselect_b32 s20, s8, s36
	s_ashr_i32 s93, s92, 31
	s_lshl_b64 s[26:27], s[92:93], 19
	s_add_u32 s26, s15, s26
	s_addc_u32 s27, s68, s27
	s_and_b64 s[52:53], s[60:61], exec
	s_cselect_b32 s25, s27, s35
	s_cselect_b32 s62, s26, s34
	s_add_u32 s63, s34, 0x100
	s_addc_u32 s64, s35, 0
	s_add_u32 s34, s36, 0x40080
	s_addc_u32 s35, s37, 0
	s_mov_b32 s65, -2
	s_add_u32 s36, s34, 0xfffc0080
	s_addc_u32 s37, s35, -1
	s_add_i32 s75, 0, 0x10000
	s_cmp_eq_u32 s65, 12
	s_cselect_b32 s53, s17, s37
	s_cselect_b32 s52, s20, s36
	s_cselect_b32 s37, s25, s64
	s_cselect_b32 s36, s62, s63
	s_add_i32 s89, 0, 0x14000
	v_add_u32_e32 v156, s75, v218
	v_add_u32_e32 v172, s89, v218
	ds_read_b128 v[128:131], v156
	ds_read_b128 v[132:135], v156 offset:1024
	ds_read_b128 v[152:155], v156 offset:2048
	ds_read_b128 v[156:159], v156 offset:3072
	ds_read_b128 v[160:163], v172
	ds_read_b128 v[164:167], v172 offset:1024
	ds_read_b128 v[168:171], v172 offset:2048
	ds_read_b128 v[182:185], v172 offset:3072
	v_lshl_add_u64 v[230:231], s[34:35], 0, v[150:151]
	s_add_i32 m0, s56, 0xc000
	ds_read_b128 v[186:189], v220
	ds_read_b128 v[190:193], v220 offset:1024
	ds_read_b128 v[194:197], v220 offset:2048
	ds_read_b128 v[198:201], v220 offset:3072
	ds_read_b128 v[202:205], v220 offset:4096
	ds_read_b128 v[206:209], v220 offset:5120
	ds_read_b128 v[222:225], v220 offset:6144
	ds_read_b128 v[226:229], v220 offset:7168
	global_load_lds_dwordx4 v[230:231], off
	v_lshl_add_u64 v[230:231], s[34:35], 0, v[148:149]
	s_add_i32 m0, s56, 0xe000
	s_nop 0
	global_load_lds_dwordx4 v[230:231], off
	s_waitcnt vmcnt(8)
	s_waitcnt lgkmcnt(0)
	s_barrier
	s_setprio 1
	s_waitcnt lgkmcnt(0)
	v_mfma_f32_16x16x32_bf16 v[124:127], v[128:131], v[186:189], 0
	v_mfma_f32_16x16x32_bf16 v[120:123], v[152:155], v[186:189], 0
	v_mfma_f32_16x16x32_bf16 v[108:111], v[128:131], v[194:197], 0
	v_mfma_f32_16x16x32_bf16 v[104:107], v[152:155], v[194:197], 0
	v_mfma_f32_16x16x32_bf16 v[92:95], v[128:131], v[202:205], 0
	v_mfma_f32_16x16x32_bf16 v[88:91], v[152:155], v[202:205], 0
	v_mfma_f32_16x16x32_bf16 v[76:79], v[128:131], v[222:225], 0
	v_mfma_f32_16x16x32_bf16 v[72:75], v[152:155], v[222:225], 0
	v_mfma_f32_16x16x32_bf16 v[124:127], v[132:135], v[190:193], v[124:127]
	v_mfma_f32_16x16x32_bf16 v[120:123], v[156:159], v[190:193], v[120:123]
	v_mfma_f32_16x16x32_bf16 v[108:111], v[132:135], v[198:201], v[108:111]
	v_mfma_f32_16x16x32_bf16 v[104:107], v[156:159], v[198:201], v[104:107]
	v_mfma_f32_16x16x32_bf16 v[92:95], v[132:135], v[206:209], v[92:95]
	v_mfma_f32_16x16x32_bf16 v[88:91], v[156:159], v[206:209], v[88:91]
	v_mfma_f32_16x16x32_bf16 v[76:79], v[132:135], v[226:229], v[76:79]
	v_mfma_f32_16x16x32_bf16 v[72:75], v[156:159], v[226:229], v[72:75]
	s_setprio 0
	s_setprio 1
	v_mfma_f32_16x16x32_bf16 v[116:119], v[160:163], v[186:189], 0
	v_mfma_f32_16x16x32_bf16 v[112:115], v[168:171], v[186:189], 0
	v_mfma_f32_16x16x32_bf16 v[100:103], v[160:163], v[194:197], 0
	v_mfma_f32_16x16x32_bf16 v[96:99], v[168:171], v[194:197], 0
	v_mfma_f32_16x16x32_bf16 v[84:87], v[160:163], v[202:205], 0
	v_mfma_f32_16x16x32_bf16 v[80:83], v[168:171], v[202:205], 0
	v_mfma_f32_16x16x32_bf16 v[68:71], v[160:163], v[222:225], 0
	v_mfma_f32_16x16x32_bf16 v[64:67], v[168:171], v[222:225], 0
	v_mfma_f32_16x16x32_bf16 v[116:119], v[164:167], v[190:193], v[116:119]
	v_mfma_f32_16x16x32_bf16 v[112:115], v[182:185], v[190:193], v[112:115]
	v_mfma_f32_16x16x32_bf16 v[100:103], v[164:167], v[198:201], v[100:103]
	v_mfma_f32_16x16x32_bf16 v[96:99], v[182:185], v[198:201], v[96:99]
	v_mfma_f32_16x16x32_bf16 v[84:87], v[164:167], v[206:209], v[84:87]
	v_mfma_f32_16x16x32_bf16 v[80:83], v[182:185], v[206:209], v[80:83]
	v_mfma_f32_16x16x32_bf16 v[68:71], v[164:167], v[226:229], v[68:71]
	v_mfma_f32_16x16x32_bf16 v[64:67], v[182:185], v[226:229], v[64:67]
	s_setprio 0
	s_barrier
	s_add_i32 s75, s75, s95
	v_lshl_add_u64 v[230:231], s[36:37], 0, v[138:139]
	s_mov_b32 m0, s75
	ds_read_b128 v[186:189], v220 offset:16384
	ds_read_b128 v[190:193], v220 offset:17408
	ds_read_b128 v[194:197], v220 offset:18432
	ds_read_b128 v[198:201], v220 offset:19456
	ds_read_b128 v[202:205], v220 offset:20480
	ds_read_b128 v[206:209], v220 offset:21504
	ds_read_b128 v[222:225], v220 offset:22528
	ds_read_b128 v[226:229], v220 offset:23552
	global_load_lds_dwordx4 v[230:231], off
	s_add_i32 m0, s75, 0x2000
	s_add_u32 s90, s36, 0x40000
	v_lshl_add_u64 v[232:233], s[36:37], 0, v[142:143]
	s_addc_u32 s91, s37, 0
	s_add_i32 s75, s89, s95
	global_load_lds_dwordx4 v[232:233], off
	v_lshl_add_u64 v[234:235], s[90:91], 0, v[138:139]
	s_mov_b32 m0, s75
	v_lshl_add_u64 v[236:237], s[52:53], 0, v[140:141]
	global_load_lds_dwordx4 v[234:235], off
	v_lshl_add_u64 v[234:235], s[90:91], 0, v[142:143]
	s_add_i32 m0, s75, 0x2000
	s_nop 0
	global_load_lds_dwordx4 v[234:235], off
	v_lshl_add_u64 v[234:235], s[52:53], 0, v[136:137]
	s_mov_b32 m0, s56
	s_nop 0
	global_load_lds_dwordx4 v[234:235], off
	s_mov_b32 m0, s57
	s_nop 0
	global_load_lds_dwordx4 v[236:237], off
	s_waitcnt vmcnt(8)
	s_waitcnt lgkmcnt(0)
	s_barrier
; #define PG8_STAGE(bufoff, gbase, voff) do { _Pragma("unroll") for (int _i = 0; _i < 2; ++_i) \
;         __builtin_amdgcn_global_load_lds((const GAS unsigned*)((const GAS char*)(gbase) + (voff)[_i]), (LAS unsigned*)(lds + (bufoff) + ldsw + _i * 8192), 16, 0, 0); } while (0)
; #define PG8_LDA(dst, b, h) do { _Pragma("unroll") for (int m = 0; m < 4; ++m) _Pragma("unroll") for (int k = 0; k < 2; ++k) dst[m][k] = *(const LAS bf16x8*)(lds + PG8_SA(b, h) + aoff + m * 2048 + k * 1024); } while (0)
; #define PG8_LDB(dst, b, h) do { _Pragma("unroll") for (int n = 0; n < 2; ++n) _Pragma("unroll") for (int k = 0; k < 2; ++k) dst[n][k] = *(const LAS bf16x8*)(lds + PG8_SB(b, h) + boff + n * 2048 + k * 1024); } while (0)
; #define PG8_MMA(ai, bj, At, Bt) do { __builtin_amdgcn_s_setprio(1); _Pragma("unroll") for (int m = 0; m < 4; ++m) _Pragma("unroll") for (int n = 0; n < 2; ++n) _Pragma("unroll") for (int k = 0; k < 2; ++k) \
;         acc[ai][bj][m][n] = __builtin_amdgcn_mfma_f32_16x16x32_bf16(Bt[n][k], At[m][k], acc[ai][bj][m][n], 0, 0, 0); __builtin_amdgcn_s_setprio(0); } while (0)
; #define PG8_WAIT_V(n) asm volatile("s_waitcnt vmcnt(" #n ")" ::: "memory")
; #define PG8_WAIT_L(n) asm volatile("s_waitcnt lgkmcnt(" #n ")" ::: "memory")
; #define PG8_BAR __builtin_amdgcn_s_barrier()
; #define PG8_SCHED __builtin_amdgcn_sched_barrier(0)
;     ...
;             PG8_WAIT_V(8); PG8_WAIT_L(0); PG8_BAR; PG8_MMA(0, 0, At, B0); PG8_MMA(0, 1, At, B1); PG8_BAR; PG8_SCHED;
;             PG8_LDA(At, 0, 1); PG8_STAGE(PG8_SB(0, 0), b2, voffB); PG8_STAGE(PG8_SB(0, 1), b2 + hstep, voffB); PG8_STAGE(PG8_SA(0, 0), a2, voffA);
;             PG8_WAIT_V(8); PG8_WAIT_L(0); PG8_BAR; PG8_MMA(1, 0, At, B0); PG8_MMA(1, 1, At, B1); PG8_BAR; PG8_SCHED;
;             PG8_LDB(B0, 1, 0); PG8_LDB(B1, 1, 1); PG8_SCHED; PG8_LDA(At, 1, 0); PG8_STAGE(PG8_SA(0, 1), a2 + hstep, voffA);
;             PG8_WAIT_V(8); PG8_WAIT_L(0); PG8_BAR; PG8_MMA(0, 0, At, B0); PG8_MMA(0, 1, At, B1); PG8_BAR; PG8_SCHED;
	s_setprio 1
	s_waitcnt lgkmcnt(0)
	v_mfma_f32_16x16x32_bf16 v[60:63], v[128:131], v[186:189], 0
	v_mfma_f32_16x16x32_bf16 v[56:59], v[152:155], v[186:189], 0
	v_mfma_f32_16x16x32_bf16 v[44:47], v[128:131], v[194:197], 0
	v_mfma_f32_16x16x32_bf16 v[40:43], v[152:155], v[194:197], 0
	v_mfma_f32_16x16x32_bf16 v[28:31], v[128:131], v[202:205], 0
	v_mfma_f32_16x16x32_bf16 v[24:27], v[152:155], v[202:205], 0
	v_mfma_f32_16x16x32_bf16 v[12:15], v[128:131], v[222:225], 0
	v_mfma_f32_16x16x32_bf16 v[8:11], v[152:155], v[222:225], 0
	v_mfma_f32_16x16x32_bf16 v[60:63], v[132:135], v[190:193], v[60:63]
	v_mfma_f32_16x16x32_bf16 v[56:59], v[156:159], v[190:193], v[56:59]
	v_mfma_f32_16x16x32_bf16 v[44:47], v[132:135], v[198:201], v[44:47]
	v_mfma_f32_16x16x32_bf16 v[40:43], v[156:159], v[198:201], v[40:43]
	v_mfma_f32_16x16x32_bf16 v[28:31], v[132:135], v[206:209], v[28:31]
	v_mfma_f32_16x16x32_bf16 v[24:27], v[156:159], v[206:209], v[24:27]
	v_mfma_f32_16x16x32_bf16 v[12:15], v[132:135], v[226:229], v[12:15]
	v_mfma_f32_16x16x32_bf16 v[8:11], v[156:159], v[226:229], v[8:11]
	s_setprio 0
	s_setprio 1
	v_mfma_f32_16x16x32_bf16 v[52:55], v[160:163], v[186:189], 0
	v_mfma_f32_16x16x32_bf16 v[48:51], v[168:171], v[186:189], 0
	v_mfma_f32_16x16x32_bf16 v[36:39], v[160:163], v[194:197], 0
	v_mfma_f32_16x16x32_bf16 v[32:35], v[168:171], v[194:197], 0
	v_mfma_f32_16x16x32_bf16 v[20:23], v[160:163], v[202:205], 0
	v_mfma_f32_16x16x32_bf16 v[16:19], v[168:171], v[202:205], 0
	v_mfma_f32_16x16x32_bf16 v[4:7], v[160:163], v[222:225], 0
	v_mfma_f32_16x16x32_bf16 v[0:3], v[168:171], v[222:225], 0
	v_mfma_f32_16x16x32_bf16 v[52:55], v[164:167], v[190:193], v[52:55]
	v_mfma_f32_16x16x32_bf16 v[48:51], v[182:185], v[190:193], v[48:51]
	v_mfma_f32_16x16x32_bf16 v[36:39], v[164:167], v[198:201], v[36:39]
	v_mfma_f32_16x16x32_bf16 v[32:35], v[182:185], v[198:201], v[32:35]
	v_mfma_f32_16x16x32_bf16 v[20:23], v[164:167], v[206:209], v[20:23]
	v_mfma_f32_16x16x32_bf16 v[16:19], v[182:185], v[206:209], v[16:19]
	v_mfma_f32_16x16x32_bf16 v[4:7], v[164:167], v[226:229], v[4:7]
	v_mfma_f32_16x16x32_bf16 v[0:3], v[182:185], v[226:229], v[0:3]
	s_setprio 0
	s_barrier
	s_add_i32 s75, 0, 0x18000
	s_add_i32 s89, 0, 0x1c000
	v_add_u32_e32 v156, s75, v218
	v_add_u32_e32 v172, s89, v218
	ds_read_b128 v[128:131], v156
	ds_read_b128 v[132:135], v156 offset:1024
	ds_read_b128 v[152:155], v156 offset:2048
	ds_read_b128 v[156:159], v156 offset:3072
	ds_read_b128 v[160:163], v172
	ds_read_b128 v[164:167], v172 offset:1024
	ds_read_b128 v[168:171], v172 offset:2048
	ds_read_b128 v[182:185], v172 offset:3072
	s_add_u32 s52, s52, 0x40000
	s_addc_u32 s53, s53, 0
	s_mov_b32 m0, s69
	v_lshl_add_u64 v[238:239], s[52:53], 0, v[136:137]
	ds_read_b128 v[186:189], v220 offset:32768
	ds_read_b128 v[190:193], v220 offset:33792
	ds_read_b128 v[194:197], v220 offset:34816
	ds_read_b128 v[198:201], v220 offset:35840
	ds_read_b128 v[202:205], v220 offset:36864
	ds_read_b128 v[206:209], v220 offset:37888
	ds_read_b128 v[222:225], v220 offset:38912
	ds_read_b128 v[226:229], v220 offset:39936
	global_load_lds_dwordx4 v[238:239], off
	v_lshl_add_u64 v[238:239], s[52:53], 0, v[140:141]
	s_mov_b32 m0, s66
	s_nop 0
	global_load_lds_dwordx4 v[238:239], off
	s_waitcnt vmcnt(8)
	s_waitcnt lgkmcnt(0)
	s_barrier
	s_setprio 1
	s_waitcnt lgkmcnt(0)
	v_mfma_f32_16x16x32_bf16 v[124:127], v[128:131], v[186:189], v[124:127]
	v_mfma_f32_16x16x32_bf16 v[120:123], v[152:155], v[186:189], v[120:123]
	v_mfma_f32_16x16x32_bf16 v[108:111], v[128:131], v[194:197], v[108:111]
	v_mfma_f32_16x16x32_bf16 v[104:107], v[152:155], v[194:197], v[104:107]
	v_mfma_f32_16x16x32_bf16 v[92:95], v[128:131], v[202:205], v[92:95]
	v_mfma_f32_16x16x32_bf16 v[88:91], v[152:155], v[202:205], v[88:91]
	v_mfma_f32_16x16x32_bf16 v[76:79], v[128:131], v[222:225], v[76:79]
	v_mfma_f32_16x16x32_bf16 v[72:75], v[152:155], v[222:225], v[72:75]
	v_mfma_f32_16x16x32_bf16 v[124:127], v[132:135], v[190:193], v[124:127]
	v_mfma_f32_16x16x32_bf16 v[120:123], v[156:159], v[190:193], v[120:123]
	v_mfma_f32_16x16x32_bf16 v[108:111], v[132:135], v[198:201], v[108:111]
	v_mfma_f32_16x16x32_bf16 v[104:107], v[156:159], v[198:201], v[104:107]
	v_mfma_f32_16x16x32_bf16 v[92:95], v[132:135], v[206:209], v[92:95]
	v_mfma_f32_16x16x32_bf16 v[88:91], v[156:159], v[206:209], v[88:91]
	v_mfma_f32_16x16x32_bf16 v[76:79], v[132:135], v[226:229], v[76:79]
	v_mfma_f32_16x16x32_bf16 v[72:75], v[156:159], v[226:229], v[72:75]
	s_setprio 0
	s_setprio 1
	v_mfma_f32_16x16x32_bf16 v[116:119], v[160:163], v[186:189], v[116:119]
	v_mfma_f32_16x16x32_bf16 v[112:115], v[168:171], v[186:189], v[112:115]
	v_mfma_f32_16x16x32_bf16 v[100:103], v[160:163], v[194:197], v[100:103]
	v_mfma_f32_16x16x32_bf16 v[96:99], v[168:171], v[194:197], v[96:99]
	v_mfma_f32_16x16x32_bf16 v[84:87], v[160:163], v[202:205], v[84:87]
	v_mfma_f32_16x16x32_bf16 v[80:83], v[168:171], v[202:205], v[80:83]
	v_mfma_f32_16x16x32_bf16 v[68:71], v[160:163], v[222:225], v[68:71]
	v_mfma_f32_16x16x32_bf16 v[64:67], v[168:171], v[222:225], v[64:67]
	v_mfma_f32_16x16x32_bf16 v[116:119], v[164:167], v[190:193], v[116:119]
	v_mfma_f32_16x16x32_bf16 v[112:115], v[182:185], v[190:193], v[112:115]
	v_mfma_f32_16x16x32_bf16 v[100:103], v[164:167], v[198:201], v[100:103]
	v_mfma_f32_16x16x32_bf16 v[96:99], v[182:185], v[198:201], v[96:99]
	v_mfma_f32_16x16x32_bf16 v[84:87], v[164:167], v[206:209], v[84:87]
	v_mfma_f32_16x16x32_bf16 v[80:83], v[182:185], v[206:209], v[80:83]
	v_mfma_f32_16x16x32_bf16 v[68:71], v[164:167], v[226:229], v[68:71]
	v_mfma_f32_16x16x32_bf16 v[64:67], v[182:185], v[226:229], v[64:67]
	s_setprio 0
	s_barrier
; #define PG8_STAGE(bufoff, gbase, voff) do { _Pragma("unroll") for (int _i = 0; _i < 2; ++_i) \
;         __builtin_amdgcn_global_load_lds((const GAS unsigned*)((const GAS char*)(gbase) + (voff)[_i]), (LAS unsigned*)(lds + (bufoff) + ldsw + _i * 8192), 16, 0, 0); } while (0)
; #define PG8_LDA(dst, b, h) do { _Pragma("unroll") for (int m = 0; m < 4; ++m) _Pragma("unroll") for (int k = 0; k < 2; ++k) dst[m][k] = *(const LAS bf16x8*)(lds + PG8_SA(b, h) + aoff + m * 2048 + k * 1024); } while (0)
; #define PG8_MMA(ai, bj, At, Bt) do { __builtin_amdgcn_s_setprio(1); _Pragma("unroll") for (int m = 0; m < 4; ++m) _Pragma("unroll") for (int n = 0; n < 2; ++n) _Pragma("unroll") for (int k = 0; k < 2; ++k) \
;         acc[ai][bj][m][n] = __builtin_amdgcn_mfma_f32_16x16x32_bf16(Bt[n][k], At[m][k], acc[ai][bj][m][n], 0, 0, 0); __builtin_amdgcn_s_setprio(0); } while (0)
; #define PG8_WAIT_V(n) asm volatile("s_waitcnt vmcnt(" #n ")" ::: "memory")
; #define PG8_WAIT_L(n) asm volatile("s_waitcnt lgkmcnt(" #n ")" ::: "memory")
; #define PG8_BAR __builtin_amdgcn_s_barrier()
; #define PG8_SCHED __builtin_amdgcn_sched_barrier(0)
;     ...
;             PG8_WAIT_V(8); PG8_WAIT_L(0); PG8_BAR; PG8_MMA(0, 0, At, B0); PG8_MMA(0, 1, At, B1); PG8_BAR; PG8_SCHED;
;             PG8_LDA(At, 1, 1); PG8_STAGE(PG8_SB(1, 0), b3, voffB); PG8_STAGE(PG8_SB(1, 1), b3 + hstep, voffB); PG8_STAGE(PG8_SA(1, 0), a3, voffA);
;             PG8_WAIT_V(8); PG8_WAIT_L(0); PG8_BAR; PG8_MMA(1, 0, At, B0); PG8_MMA(1, 1, At, B1); PG8_BAR; PG8_SCHED;
;         }
	s_add_i32 s52, s75, s95
	v_lshl_add_u64 v[230:231], v[230:231], 0, s[82:83]
	s_mov_b32 m0, s52
	ds_read_b128 v[186:189], v220 offset:49152
	ds_read_b128 v[190:193], v220 offset:50176
	ds_read_b128 v[194:197], v220 offset:51200
	ds_read_b128 v[198:201], v220 offset:52224
	ds_read_b128 v[202:205], v220 offset:53248
	ds_read_b128 v[206:209], v220 offset:54272
	ds_read_b128 v[222:225], v220 offset:55296
	ds_read_b128 v[226:229], v220 offset:56320
	global_load_lds_dwordx4 v[230:231], off
	s_add_i32 m0, s52, 0x2000
	s_add_u32 s36, s36, 0x40080
	v_lshl_add_u64 v[230:231], v[232:233], 0, s[82:83]
	s_addc_u32 s37, s37, 0
	s_add_i32 s52, s89, s95
	global_load_lds_dwordx4 v[230:231], off
	v_lshl_add_u64 v[230:231], s[36:37], 0, v[138:139]
	s_mov_b32 m0, s52
	s_nop 0
	global_load_lds_dwordx4 v[230:231], off
	v_lshl_add_u64 v[230:231], s[36:37], 0, v[142:143]
	s_add_i32 m0, s52, 0x2000
	s_nop 0
	global_load_lds_dwordx4 v[230:231], off
	v_lshl_add_u64 v[230:231], v[234:235], 0, s[82:83]
	s_mov_b32 m0, s67
	s_nop 0
	global_load_lds_dwordx4 v[230:231], off
	v_lshl_add_u64 v[230:231], v[236:237], 0, s[82:83]
	s_mov_b32 m0, s12
	s_nop 0
	global_load_lds_dwordx4 v[230:231], off
	s_waitcnt vmcnt(8)
	s_waitcnt lgkmcnt(0)
	s_barrier
	s_setprio 1
	s_waitcnt lgkmcnt(0)
	v_mfma_f32_16x16x32_bf16 v[60:63], v[128:131], v[186:189], v[60:63]
	v_mfma_f32_16x16x32_bf16 v[56:59], v[152:155], v[186:189], v[56:59]
	v_mfma_f32_16x16x32_bf16 v[44:47], v[128:131], v[194:197], v[44:47]
	v_mfma_f32_16x16x32_bf16 v[40:43], v[152:155], v[194:197], v[40:43]
	v_mfma_f32_16x16x32_bf16 v[28:31], v[128:131], v[202:205], v[28:31]
	v_mfma_f32_16x16x32_bf16 v[24:27], v[152:155], v[202:205], v[24:27]
	v_mfma_f32_16x16x32_bf16 v[12:15], v[128:131], v[222:225], v[12:15]
	v_mfma_f32_16x16x32_bf16 v[8:11], v[152:155], v[222:225], v[8:11]
	v_mfma_f32_16x16x32_bf16 v[60:63], v[132:135], v[190:193], v[60:63]
	v_mfma_f32_16x16x32_bf16 v[56:59], v[156:159], v[190:193], v[56:59]
	v_mfma_f32_16x16x32_bf16 v[44:47], v[132:135], v[198:201], v[44:47]
	v_mfma_f32_16x16x32_bf16 v[40:43], v[156:159], v[198:201], v[40:43]
	v_mfma_f32_16x16x32_bf16 v[28:31], v[132:135], v[206:209], v[28:31]
	v_mfma_f32_16x16x32_bf16 v[24:27], v[156:159], v[206:209], v[24:27]
	v_mfma_f32_16x16x32_bf16 v[12:15], v[132:135], v[226:229], v[12:15]
	v_mfma_f32_16x16x32_bf16 v[8:11], v[156:159], v[226:229], v[8:11]
	s_setprio 0
	s_setprio 1
	v_mfma_f32_16x16x32_bf16 v[52:55], v[160:163], v[186:189], v[52:55]
	v_mfma_f32_16x16x32_bf16 v[48:51], v[168:171], v[186:189], v[48:51]
	v_mfma_f32_16x16x32_bf16 v[36:39], v[160:163], v[194:197], v[36:39]
	v_mfma_f32_16x16x32_bf16 v[32:35], v[168:171], v[194:197], v[32:35]
	v_mfma_f32_16x16x32_bf16 v[20:23], v[160:163], v[202:205], v[20:23]
	v_mfma_f32_16x16x32_bf16 v[16:19], v[168:171], v[202:205], v[16:19]
	v_mfma_f32_16x16x32_bf16 v[4:7], v[160:163], v[222:225], v[4:7]
	v_mfma_f32_16x16x32_bf16 v[0:3], v[168:171], v[222:225], v[0:3]
	v_mfma_f32_16x16x32_bf16 v[52:55], v[164:167], v[190:193], v[52:55]
	v_mfma_f32_16x16x32_bf16 v[48:51], v[182:185], v[190:193], v[48:51]
	v_mfma_f32_16x16x32_bf16 v[36:39], v[164:167], v[198:201], v[36:39]
	v_mfma_f32_16x16x32_bf16 v[32:35], v[182:185], v[198:201], v[32:35]
	v_mfma_f32_16x16x32_bf16 v[20:23], v[164:167], v[206:209], v[20:23]
	v_mfma_f32_16x16x32_bf16 v[16:19], v[182:185], v[206:209], v[16:19]
	v_mfma_f32_16x16x32_bf16 v[4:7], v[164:167], v[226:229], v[4:7]
	v_mfma_f32_16x16x32_bf16 v[0:3], v[182:185], v[226:229], v[0:3]
	s_setprio 0
	s_barrier
	s_add_i32 s65, s65, 2
	s_add_u32 s63, s63, 0x100
	s_addc_u32 s64, s64, 0
	s_add_u32 s34, s34, 0x100
	s_addc_u32 s35, s35, 0
